# m1 attention-prep job: norm-weight and rope-table loads of the three vectors per iteration issued at the top with the u-row loads (one wait) instead of six exec-masked load-wait round trips
# speedup vs baseline: 1.0390x; 1.0067x over previous
.LBB0_301:
	v_mul_hi_i32 v0, v17, s76
	v_lshrrev_b32_e32 v1, 31, v0
	v_add_u32_e32 v2, v0, v1
	s_movk_i32 s0, 0xffe8
	v_mad_u64_u32 v[0:1], s[0:1], v2, s0, v[22:23]
	v_cmp_lt_i32_e64 s[8:9], 11, v0
	v_mul_lo_u32 v45, v2, 24
	v_readlane_b32 s60, v254, 12
	v_cndmask_b32_e64 v29, 0, -12, s[8:9]
	v_sub_u32_e32 v0, v29, v45
	v_readlane_b32 s66, v254, 18
	v_readlane_b32 s67, v254, 19
	v_add_u32_e32 v46, s24, v2
	v_add_u32_e32 v28, v22, v0
	v_mov_b64_e32 v[0:1], s[66:67]
	v_mad_i64_i32 v[2:3], s[0:1], v46, s77, v[0:1]
	v_cndmask_b32_e64 v112, v123, v124, s[8:9]
	v_lshlrev_b32_e32 v4, 7, v28
	v_lshl_add_u64 v[2:3], v[2:3], 0, v[112:113]
	v_ashrrev_i32_e32 v5, 31, v4
	v_lshl_add_u64 v[2:3], v[4:5], 1, v[2:3]
	v_lshlrev_b32_e32 v112, 1, v16
	v_lshl_add_u64 v[2:3], v[2:3], 0, v[112:113]
	global_load_dwordx4 v[12:15], v[2:3], off
	v_add_u32_e32 v2, 8, v17
	v_mul_hi_i32 v3, v2, s76
	v_lshrrev_b32_e32 v4, 31, v3
	v_add_u32_e32 v3, v3, v4
	v_mul_lo_u32 v4, v3, 6
	v_sub_u32_e32 v2, v2, v4
	v_lshl_or_b32 v2, v2, 2, v23
	v_cmp_lt_i32_e64 s[6:7], 11, v2
	v_add_u32_e32 v44, s24, v3
	v_mov_b32_e32 v5, v113
	v_cndmask_b32_e64 v3, 0, -12, s[6:7]
	v_add_u32_e32 v43, v3, v2
	v_mad_i64_i32 v[2:3], s[0:1], v44, s77, v[0:1]
	v_cndmask_b32_e64 v4, v123, v124, s[6:7]
	v_lshl_add_u64 v[2:3], v[2:3], 0, v[4:5]
	v_lshlrev_b32_e32 v4, 7, v43
	v_ashrrev_i32_e32 v5, 31, v4
	v_lshl_add_u64 v[2:3], v[4:5], 1, v[2:3]
	v_lshl_add_u64 v[2:3], v[2:3], 0, v[112:113]
	global_load_dwordx4 v[4:7], v[2:3], off
	v_add_u32_e32 v2, 16, v17
	v_mul_hi_i32 v3, v2, s76
	v_lshrrev_b32_e32 v8, 31, v3
	v_add_u32_e32 v3, v3, v8
	v_mul_lo_u32 v8, v3, 6
	v_sub_u32_e32 v2, v2, v8
	v_lshl_or_b32 v2, v2, 2, v23
	v_cmp_lt_i32_e64 s[4:5], 11, v2
	v_add_u32_e32 v42, s24, v3
	v_mad_i64_i32 v[0:1], s[0:1], v42, s77, v[0:1]
	v_cndmask_b32_e64 v3, 0, -12, s[4:5]
	v_add_u32_e32 v41, v3, v2
	v_cndmask_b32_e64 v2, v123, v124, s[4:5]
	v_mov_b32_e32 v3, v113
	v_lshl_add_u64 v[0:1], v[0:1], 0, v[2:3]
	v_lshlrev_b32_e32 v2, 7, v41
	v_ashrrev_i32_e32 v3, 31, v2
	v_lshl_add_u64 v[0:1], v[2:3], 1, v[0:1]
	v_lshl_add_u64 v[0:1], v[0:1], 0, v[112:113]
	global_load_dwordx4 v[0:3], v[0:1], off
	v_cmp_gt_i32_e64 s[10:11], 10, v28
	v_cmp_gt_i32_e64 s[12:13], 8, v28
	v_cmp_lt_i32_e64 s[14:15], 7, v28
	s_and_b64 s[0:1], s[8:9], s[10:11]
	v_readlane_b32 s61, v254, 13
	v_readlane_b32 s62, v254, 14
	v_readlane_b32 s63, v254, 15
	v_readlane_b32 s64, v254, 16
	v_readlane_b32 s65, v254, 17
	v_readlane_b32 s68, v254, 20
	v_readlane_b32 s69, v254, 21
	v_readlane_b32 s70, v254, 22
	v_readlane_b32 s71, v254, 23
	v_readlane_b32 s72, v254, 24
	v_readlane_b32 s73, v254, 25
	v_readlane_b32 s74, v254, 26
	v_readlane_b32 s75, v254, 27
	v_lshlrev_b32_e32 v210, 2, v16
	v_mov_b32_e32 v211, 0
	v_cmp_gt_i32_e64 s[98:99], 8, v28
	v_mov_b32_e32 v206, s20
	v_mov_b32_e32 v207, s2
	v_mov_b32_e32 v208, s21
	v_mov_b32_e32 v209, s3
	v_cndmask_b32_e64 v206, v207, v206, s[98:99]
	v_cndmask_b32_e64 v207, v209, v208, s[98:99]
	v_lshl_add_u64 v[206:207], v[206:207], 0, v[210:211]
	global_load_dwordx4 v[130:133], v[206:207], off
	global_load_dwordx4 v[134:137], v[206:207], off offset:16
	s_cbranch_vccz .Lprepa_norope0
	v_and_b32_e32 v208, s55, v46
	v_lshlrev_b32_e32 v208, 9, v208
	v_mov_b32_e32 v209, 0
	v_lshl_add_u64 v[208:209], v[20:21], 0, v[208:209]
	global_load_dwordx4 v[138:141], v[208:209], off offset:48
	global_load_dwordx4 v[142:145], v[208:209], off offset:32
	global_load_dwordx4 v[146:149], v[208:209], off offset:16
	global_load_dwordx4 v[150:153], v[208:209], off
.Lprepa_norope0:
	v_cmp_gt_i32_e64 s[98:99], 8, v43
	v_mov_b32_e32 v206, s20
	v_mov_b32_e32 v207, s2
	v_mov_b32_e32 v208, s21
	v_mov_b32_e32 v209, s3
	v_cndmask_b32_e64 v206, v207, v206, s[98:99]
	v_cndmask_b32_e64 v207, v209, v208, s[98:99]
	v_lshl_add_u64 v[206:207], v[206:207], 0, v[210:211]
	global_load_dwordx4 v[154:157], v[206:207], off
	global_load_dwordx4 v[158:161], v[206:207], off offset:16
	s_cbranch_vccz .Lprepa_norope1
	v_and_b32_e32 v208, s55, v44
	v_lshlrev_b32_e32 v208, 9, v208
	v_mov_b32_e32 v209, 0
	v_lshl_add_u64 v[208:209], v[20:21], 0, v[208:209]
	global_load_dwordx4 v[162:165], v[208:209], off offset:48
	global_load_dwordx4 v[166:169], v[208:209], off offset:32
	global_load_dwordx4 v[170:173], v[208:209], off offset:16
	global_load_dwordx4 v[174:177], v[208:209], off
.Lprepa_norope1:
	v_cmp_gt_i32_e64 s[98:99], 8, v41
	v_mov_b32_e32 v206, s20
	v_mov_b32_e32 v207, s2
	v_mov_b32_e32 v208, s21
	v_mov_b32_e32 v209, s3
	v_cndmask_b32_e64 v206, v207, v206, s[98:99]
	v_cndmask_b32_e64 v207, v209, v208, s[98:99]
	v_lshl_add_u64 v[206:207], v[206:207], 0, v[210:211]
	global_load_dwordx4 v[182:185], v[206:207], off
	global_load_dwordx4 v[186:189], v[206:207], off offset:16
	s_cbranch_vccz .Lprepa_norope2
	v_and_b32_e32 v208, s55, v42
	v_lshlrev_b32_e32 v208, 9, v208
	v_mov_b32_e32 v209, 0
	v_lshl_add_u64 v[208:209], v[20:21], 0, v[208:209]
	global_load_dwordx4 v[190:193], v[208:209], off offset:48
	global_load_dwordx4 v[194:197], v[208:209], off offset:32
	global_load_dwordx4 v[198:201], v[208:209], off offset:16
	global_load_dwordx4 v[202:205], v[208:209], off
.Lprepa_norope2:
	s_waitcnt vmcnt(0)
	v_lshlrev_b32_e32 v8, 16, v12
	v_and_b32_e32 v9, 0xffff0000, v12
	v_lshlrev_b32_e32 v10, 16, v13
	v_and_b32_e32 v11, 0xffff0000, v13
	v_pk_mul_f32 v[24:25], v[8:9], v[8:9]
	v_pk_mul_f32 v[26:27], v[10:11], v[10:11]
	v_add_f32_e32 v24, v24, v25
	v_lshlrev_b32_e32 v12, 16, v14
	v_and_b32_e32 v13, 0xffff0000, v14
	v_add_f32_e32 v24, v24, v26
	v_pk_mul_f32 v[30:31], v[12:13], v[12:13]
	v_add_f32_e32 v24, v27, v24
	v_lshlrev_b32_e32 v14, 16, v15
	v_and_b32_e32 v15, 0xffff0000, v15
	v_add_f32_e32 v24, v30, v24
	v_pk_mul_f32 v[32:33], v[14:15], v[14:15]
	v_add_f32_e32 v24, v31, v24
	v_add_f32_e32 v24, v32, v24
	v_add_f32_e32 v24, v33, v24
	ds_bpermute_b32 v25, v37, v24
	s_waitcnt lgkmcnt(0)
	v_add_f32_e32 v24, v24, v25
	ds_bpermute_b32 v25, v38, v24
	s_waitcnt lgkmcnt(0)
	v_add_f32_e32 v24, v24, v25
	ds_bpermute_b32 v25, v39, v24
	s_waitcnt lgkmcnt(0)
	v_add_f32_e32 v25, v24, v25
	ds_bpermute_b32 v26, v40, v25
	v_lshlrev_b32_e32 v24, 2, v16
	s_and_saveexec_b64 s[58:59], s[0:1]
	s_cbranch_execz .LBB0_303
	s_waitcnt lgkmcnt(0)
	v_add_f32_e32 v25, v25, v26
	v_fmamk_f32 v25, v25, 0x3c000000, v115
	v_cmp_gt_f32_e64 s[0:1], s78, v25
	v_mul_f32_e32 v26, 0x4b800000, v25
	v_mov_b32_e32 v27, s21
	v_cndmask_b32_e64 v25, v25, v26, s[0:1]
	v_rsq_f32_e32 v25, v25
	s_nop 0
	v_mul_f32_e32 v26, 0x45800000, v25
	v_cndmask_b32_e64 v26, v25, v26, s[0:1]
	v_mov_b32_e32 v25, s3
	v_cndmask_b32_e64 v31, v25, v27, s[12:13]
	v_mov_b32_e32 v25, s2
	v_mov_b32_e32 v27, s20
	v_cndmask_b32_e64 v30, v25, v27, s[12:13]
	v_mov_b32_e32 v25, v113
	v_lshl_add_u64 v[34:35], v[30:31], 0, v[24:25]
	v_mov_b32_e32 v30, v130
	v_mov_b32_e32 v31, v131
	v_mov_b32_e32 v32, v132
	v_mov_b32_e32 v33, v133
	v_mov_b32_e32 v48, v134
	v_mov_b32_e32 v49, v135
	v_mov_b32_e32 v50, v136
	v_mov_b32_e32 v51, v137
	v_pk_mul_f32 v[32:33], v[26:27], v[32:33] op_sel_hi:[0,1]
	v_pk_mul_f32 v[34:35], v[26:27], v[50:51] op_sel_hi:[0,1]
	v_pk_mul_f32 v[30:31], v[26:27], v[30:31] op_sel_hi:[0,1]
	v_pk_mul_f32 v[26:27], v[26:27], v[48:49] op_sel_hi:[0,1]
	v_pk_mul_f32 v[14:15], v[34:35], v[14:15]
	v_pk_mul_f32 v[10:11], v[32:33], v[10:11]
	v_pk_mul_f32 v[12:13], v[26:27], v[12:13]
	v_pk_mul_f32 v[8:9], v[30:31], v[8:9]
.LBB0_303:
	s_or_b64 exec, exec, s[58:59]
	ds_bpermute_b32 v34, v39, v8
	ds_bpermute_b32 v35, v39, v9
	ds_bpermute_b32 v32, v39, v10
	ds_bpermute_b32 v33, v39, v11
	ds_bpermute_b32 v30, v39, v12
	ds_bpermute_b32 v31, v39, v13
	ds_bpermute_b32 v47, v39, v14
	ds_bpermute_b32 v25, v39, v15
	v_and_b32_e32 v28, s55, v46
	s_and_b64 s[58:59], vcc, s[10:11]
	s_waitcnt lgkmcnt(8)
	v_lshlrev_b32_e32 v26, 9, v28
	s_and_saveexec_b64 s[0:1], s[58:59]
	s_cbranch_execz .LBB0_305
	v_mov_b32_e32 v27, v113
	v_lshl_add_u64 v[60:61], v[20:21], 0, v[26:27]
	v_mov_b32_e32 v48, v138
	v_mov_b32_e32 v49, v139
	v_mov_b32_e32 v50, v140
	v_mov_b32_e32 v51, v141
	v_mov_b32_e32 v52, v142
	v_mov_b32_e32 v53, v143
	v_mov_b32_e32 v54, v144
	v_mov_b32_e32 v55, v145
	v_mov_b32_e32 v56, v146
	v_mov_b32_e32 v57, v147
	v_mov_b32_e32 v58, v148
	v_mov_b32_e32 v59, v149
	v_mov_b32_e32 v60, v150
	v_mov_b32_e32 v61, v151
	v_mov_b32_e32 v62, v152
	v_mov_b32_e32 v63, v153
	s_waitcnt lgkmcnt(6)
	v_pk_mul_f32 v[34:35], v[18:19], v[34:35]
	s_waitcnt lgkmcnt(4)
	v_pk_mul_f32 v[32:33], v[18:19], v[32:33]
	s_waitcnt lgkmcnt(2)
	v_pk_mul_f32 v[30:31], v[18:19], v[30:31]
	s_waitcnt lgkmcnt(1)
	v_mul_f32_e32 v27, v18, v47
	s_nop 0
	v_mul_f32_e32 v14, v14, v48
	v_mul_f32_e32 v48, v27, v49
	s_nop 0
	v_mov_b32_e32 v64, v60
	v_mov_b32_e32 v65, v62
	v_mov_b32_e32 v62, v61
	v_mov_b32_e32 v60, v56
	v_mov_b32_e32 v61, v58
	v_mov_b32_e32 v58, v57
	v_mov_b32_e32 v56, v52
	v_mov_b32_e32 v57, v54
	v_mov_b32_e32 v54, v53
	s_waitcnt lgkmcnt(0)
	v_mul_f32_e32 v53, v18, v25
	v_mov_b32_e32 v52, v15
	v_pk_mul_f32 v[50:51], v[52:53], v[50:51]
	v_pk_mul_f32 v[34:35], v[34:35], v[62:63]
	v_pk_mul_f32 v[32:33], v[32:33], v[58:59]
	v_pk_mul_f32 v[30:31], v[30:31], v[54:55]
	v_mov_b32_e32 v15, v50
	v_mov_b32_e32 v49, v51
	v_pk_fma_f32 v[8:9], v[8:9], v[64:65], v[34:35]
	v_pk_fma_f32 v[10:11], v[10:11], v[60:61], v[32:33]
	v_pk_fma_f32 v[12:13], v[12:13], v[56:57], v[30:31]
	v_pk_add_f32 v[14:15], v[14:15], v[48:49]

.LBB0_317:
	s_or_b64 exec, exec, s[0:1]
	v_lshlrev_b32_e32 v8, 16, v4
	v_and_b32_e32 v9, 0xffff0000, v4
	v_lshlrev_b32_e32 v10, 16, v5
	v_and_b32_e32 v11, 0xffff0000, v5
	v_pk_mul_f32 v[12:13], v[8:9], v[8:9]
	v_pk_mul_f32 v[14:15], v[10:11], v[10:11]
	v_add_f32_e32 v12, v12, v13
	v_lshlrev_b32_e32 v4, 16, v6
	v_and_b32_e32 v5, 0xffff0000, v6
	v_add_f32_e32 v12, v12, v14
	v_pk_mul_f32 v[26:27], v[4:5], v[4:5]
	v_add_f32_e32 v12, v15, v12
	v_lshlrev_b32_e32 v6, 16, v7
	v_and_b32_e32 v7, 0xffff0000, v7
	v_add_f32_e32 v12, v26, v12
	v_pk_mul_f32 v[28:29], v[6:7], v[6:7]
	v_add_f32_e32 v12, v27, v12
	v_add_f32_e32 v12, v28, v12
	v_add_f32_e32 v12, v29, v12
	ds_bpermute_b32 v13, v37, v12
	v_cmp_gt_i32_e64 s[8:9], 10, v43
	v_cmp_gt_i32_e64 s[10:11], 8, v43
	v_cmp_lt_i32_e64 s[12:13], 7, v43
	s_and_b64 s[0:1], s[6:7], s[8:9]
	s_waitcnt lgkmcnt(0)
	v_add_f32_e32 v12, v12, v13
	ds_bpermute_b32 v13, v38, v12
	s_waitcnt lgkmcnt(0)
	v_add_f32_e32 v12, v12, v13
	ds_bpermute_b32 v13, v39, v12
	s_waitcnt lgkmcnt(0)
	v_add_f32_e32 v12, v12, v13
	ds_bpermute_b32 v13, v40, v12
	s_and_saveexec_b64 s[14:15], s[0:1]
	s_cbranch_execz .LBB0_319
	s_waitcnt lgkmcnt(0)
	v_add_f32_e32 v12, v12, v13
	v_fmamk_f32 v12, v12, 0x3c000000, v115
	v_cmp_gt_f32_e64 s[0:1], s78, v12
	v_mul_f32_e32 v13, 0x4b800000, v12
	v_mov_b32_e32 v14, s20
	v_cndmask_b32_e64 v12, v12, v13, s[0:1]
	v_rsq_f32_e32 v12, v12
	v_mov_b32_e32 v25, v113
	v_mul_f32_e32 v13, 0x45800000, v12
	v_cndmask_b32_e64 v30, v12, v13, s[0:1]
	v_mov_b32_e32 v12, s3
	v_mov_b32_e32 v13, s21
	v_cndmask_b32_e64 v13, v12, v13, s[10:11]
	v_mov_b32_e32 v12, s2
	v_cndmask_b32_e64 v12, v12, v14, s[10:11]
	v_lshl_add_u64 v[26:27], v[12:13], 0, v[24:25]
	v_mov_b32_e32 v12, v154
	v_mov_b32_e32 v13, v155
	v_mov_b32_e32 v14, v156
	v_mov_b32_e32 v15, v157
	v_mov_b32_e32 v26, v158
	v_mov_b32_e32 v27, v159
	v_mov_b32_e32 v28, v160
	v_mov_b32_e32 v29, v161
	v_pk_mul_f32 v[14:15], v[30:31], v[14:15] op_sel_hi:[0,1]
	v_pk_mul_f32 v[28:29], v[30:31], v[28:29] op_sel_hi:[0,1]
	v_pk_mul_f32 v[12:13], v[30:31], v[12:13] op_sel_hi:[0,1]
	v_pk_mul_f32 v[26:27], v[30:31], v[26:27] op_sel_hi:[0,1]
	v_pk_mul_f32 v[6:7], v[28:29], v[6:7]
	v_pk_mul_f32 v[10:11], v[14:15], v[10:11]
	v_pk_mul_f32 v[4:5], v[26:27], v[4:5]
	v_pk_mul_f32 v[8:9], v[12:13], v[8:9]
.LBB0_319:
	s_or_b64 exec, exec, s[14:15]
	ds_bpermute_b32 v30, v39, v8
	ds_bpermute_b32 v31, v39, v9
	ds_bpermute_b32 v28, v39, v10
	ds_bpermute_b32 v29, v39, v11
	ds_bpermute_b32 v26, v39, v4
	ds_bpermute_b32 v27, v39, v5
	ds_bpermute_b32 v25, v39, v6
	ds_bpermute_b32 v15, v39, v7
	v_and_b32_e32 v14, s55, v44
	s_and_b64 s[14:15], vcc, s[8:9]
	v_lshlrev_b32_e32 v12, 9, v14
	s_and_saveexec_b64 s[0:1], s[14:15]
	s_cbranch_execz .LBB0_321
	s_waitcnt lgkmcnt(0)
	v_mov_b32_e32 v13, v113
	v_lshl_add_u64 v[54:55], v[20:21], 0, v[12:13]
	v_mov_b32_e32 v32, v162
	v_mov_b32_e32 v33, v163
	v_mov_b32_e32 v34, v164
	v_mov_b32_e32 v35, v165
	v_mov_b32_e32 v46, v166
	v_mov_b32_e32 v47, v167
	v_mov_b32_e32 v48, v168
	v_mov_b32_e32 v49, v169
	v_mov_b32_e32 v50, v170
	v_mov_b32_e32 v51, v171
	v_mov_b32_e32 v52, v172
	v_mov_b32_e32 v53, v173
	v_mov_b32_e32 v54, v174
	v_mov_b32_e32 v55, v175
	v_mov_b32_e32 v56, v176
	v_mov_b32_e32 v57, v177
	v_pk_mul_f32 v[30:31], v[18:19], v[30:31]
	v_pk_mul_f32 v[28:29], v[18:19], v[28:29]
	v_pk_mul_f32 v[26:27], v[18:19], v[26:27]
	v_mul_f32_e32 v13, v18, v25
	s_nop 0
	v_mul_f32_e32 v6, v6, v32
	v_mul_f32_e32 v32, v13, v33
	v_mov_b32_e32 v58, v54
	v_mov_b32_e32 v59, v56
	v_mov_b32_e32 v56, v55
	v_mov_b32_e32 v54, v50
	v_mov_b32_e32 v55, v52
	v_mov_b32_e32 v52, v51
	v_mov_b32_e32 v50, v46
	v_mov_b32_e32 v51, v48
	v_mov_b32_e32 v48, v47
	v_mul_f32_e32 v47, v18, v15
	v_mov_b32_e32 v46, v7
	v_pk_mul_f32 v[34:35], v[46:47], v[34:35]
	v_pk_mul_f32 v[30:31], v[30:31], v[56:57]
	v_pk_mul_f32 v[28:29], v[28:29], v[52:53]
	v_pk_mul_f32 v[26:27], v[26:27], v[48:49]
	v_mov_b32_e32 v7, v34
	v_mov_b32_e32 v33, v35
	v_pk_fma_f32 v[8:9], v[8:9], v[58:59], v[30:31]
	v_pk_fma_f32 v[10:11], v[10:11], v[54:55], v[28:29]
	v_pk_fma_f32 v[4:5], v[4:5], v[50:51], v[26:27]
	v_pk_add_f32 v[6:7], v[6:7], v[32:33]

.LBB0_333:
	s_or_b64 exec, exec, s[0:1]
	s_nop 0
	v_lshlrev_b32_e32 v4, 16, v0
	v_and_b32_e32 v5, 0xffff0000, v0
	v_lshlrev_b32_e32 v6, 16, v1
	v_and_b32_e32 v7, 0xffff0000, v1
	v_pk_mul_f32 v[8:9], v[4:5], v[4:5]
	v_pk_mul_f32 v[10:11], v[6:7], v[6:7]
	v_add_f32_e32 v8, v8, v9
	v_lshlrev_b32_e32 v0, 16, v2
	v_and_b32_e32 v1, 0xffff0000, v2
	v_add_f32_e32 v8, v8, v10
	v_pk_mul_f32 v[12:13], v[0:1], v[0:1]
	v_add_f32_e32 v8, v11, v8
	v_lshlrev_b32_e32 v2, 16, v3
	v_and_b32_e32 v3, 0xffff0000, v3
	v_add_f32_e32 v8, v12, v8
	v_pk_mul_f32 v[14:15], v[2:3], v[2:3]
	v_add_f32_e32 v8, v13, v8
	v_add_f32_e32 v8, v14, v8
	v_add_f32_e32 v8, v15, v8
	ds_bpermute_b32 v9, v37, v8
	v_cmp_gt_i32_e64 s[6:7], 10, v41
	v_cmp_gt_i32_e64 s[8:9], 8, v41
	v_cmp_lt_i32_e64 s[10:11], 7, v41
	s_and_b64 s[0:1], s[4:5], s[6:7]
	s_waitcnt lgkmcnt(0)
	v_add_f32_e32 v8, v8, v9
	ds_bpermute_b32 v9, v38, v8
	s_waitcnt lgkmcnt(0)
	v_add_f32_e32 v8, v8, v9
	ds_bpermute_b32 v9, v39, v8
	s_waitcnt lgkmcnt(0)
	v_add_f32_e32 v8, v8, v9
	ds_bpermute_b32 v9, v40, v8
	s_and_saveexec_b64 s[12:13], s[0:1]
	s_cbranch_execz .LBB0_335
	s_waitcnt lgkmcnt(0)
	v_add_f32_e32 v8, v8, v9
	v_fmamk_f32 v8, v8, 0x3c000000, v115
	v_cmp_gt_f32_e64 s[0:1], s78, v8
	v_mul_f32_e32 v9, 0x4b800000, v8
	v_mov_b32_e32 v10, s20
	v_cndmask_b32_e64 v8, v8, v9, s[0:1]
	v_rsq_f32_e32 v8, v8
	v_mov_b32_e32 v25, v113
	v_mul_f32_e32 v9, 0x45800000, v8
	v_cndmask_b32_e64 v26, v8, v9, s[0:1]
	v_mov_b32_e32 v8, s3
	v_mov_b32_e32 v9, s21
	v_cndmask_b32_e64 v9, v8, v9, s[8:9]
	v_mov_b32_e32 v8, s2
	v_cndmask_b32_e64 v8, v8, v10, s[8:9]
	v_lshl_add_u64 v[12:13], v[8:9], 0, v[24:25]
	v_mov_b32_e32 v8, v182
	v_mov_b32_e32 v9, v183
	v_mov_b32_e32 v10, v184
	v_mov_b32_e32 v11, v185
	v_mov_b32_e32 v12, v186
	v_mov_b32_e32 v13, v187
	v_mov_b32_e32 v14, v188
	v_mov_b32_e32 v15, v189
	v_pk_mul_f32 v[10:11], v[26:27], v[10:11] op_sel_hi:[0,1]
	v_pk_mul_f32 v[14:15], v[26:27], v[14:15] op_sel_hi:[0,1]
	v_pk_mul_f32 v[8:9], v[26:27], v[8:9] op_sel_hi:[0,1]
	v_pk_mul_f32 v[12:13], v[26:27], v[12:13] op_sel_hi:[0,1]
	v_pk_mul_f32 v[2:3], v[14:15], v[2:3]
	v_pk_mul_f32 v[6:7], v[10:11], v[6:7]
	v_pk_mul_f32 v[0:1], v[12:13], v[0:1]
	v_pk_mul_f32 v[4:5], v[8:9], v[4:5]
.LBB0_335:
	s_or_b64 exec, exec, s[12:13]
	ds_bpermute_b32 v26, v39, v4
	ds_bpermute_b32 v27, v39, v5
	ds_bpermute_b32 v14, v39, v6
	ds_bpermute_b32 v15, v39, v7
	ds_bpermute_b32 v12, v39, v0
	ds_bpermute_b32 v13, v39, v1
	ds_bpermute_b32 v25, v39, v2
	ds_bpermute_b32 v11, v39, v3
	v_and_b32_e32 v10, s55, v42
	s_and_b64 s[12:13], vcc, s[6:7]
	v_lshlrev_b32_e32 v8, 9, v10
	s_and_saveexec_b64 s[0:1], s[12:13]
	s_cbranch_execz .LBB0_337
	s_waitcnt lgkmcnt(0)
	v_mov_b32_e32 v9, v113
	v_lshl_add_u64 v[48:49], v[20:21], 0, v[8:9]
	v_mov_b32_e32 v28, v190
	v_mov_b32_e32 v29, v191
	v_mov_b32_e32 v30, v192
	v_mov_b32_e32 v31, v193
	v_mov_b32_e32 v32, v194
	v_mov_b32_e32 v33, v195
	v_mov_b32_e32 v34, v196
	v_mov_b32_e32 v35, v197
	v_mov_b32_e32 v44, v198
	v_mov_b32_e32 v45, v199
	v_mov_b32_e32 v46, v200
	v_mov_b32_e32 v47, v201
	v_mov_b32_e32 v48, v202
	v_mov_b32_e32 v49, v203
	v_mov_b32_e32 v50, v204
	v_mov_b32_e32 v51, v205
	v_pk_mul_f32 v[26:27], v[18:19], v[26:27]
	v_pk_mul_f32 v[14:15], v[18:19], v[14:15]
	v_pk_mul_f32 v[12:13], v[18:19], v[12:13]
	v_mul_f32_e32 v9, v18, v25
	s_nop 0
	v_mul_f32_e32 v2, v2, v28
	v_mul_f32_e32 v28, v9, v29
	v_mov_b32_e32 v52, v48
	v_mov_b32_e32 v53, v50
	v_mov_b32_e32 v50, v49
	v_mov_b32_e32 v48, v44
	v_mov_b32_e32 v49, v46
	v_mov_b32_e32 v46, v45
	v_mov_b32_e32 v44, v32
	v_mov_b32_e32 v45, v34
	v_mov_b32_e32 v34, v33
	v_mul_f32_e32 v33, v18, v11
	v_mov_b32_e32 v32, v3
	v_pk_mul_f32 v[30:31], v[32:33], v[30:31]
	v_pk_mul_f32 v[26:27], v[26:27], v[50:51]
	v_pk_mul_f32 v[14:15], v[14:15], v[46:47]
	v_pk_mul_f32 v[12:13], v[12:13], v[34:35]
	v_mov_b32_e32 v3, v30
	v_mov_b32_e32 v29, v31
	v_pk_fma_f32 v[4:5], v[4:5], v[52:53], v[26:27]
	v_pk_fma_f32 v[6:7], v[6:7], v[48:49], v[14:15]
	v_pk_fma_f32 v[0:1], v[0:1], v[44:45], v[12:13]
	v_pk_add_f32 v[2:3], v[2:3], v[28:29]

.LBB0_1011:
	v_mul_hi_i32 v0, v17, s66
	v_lshrrev_b32_e32 v1, 31, v0
	v_add_u32_e32 v2, v0, v1
	s_movk_i32 s0, 0xffe8
	v_mad_u64_u32 v[0:1], s[0:1], v2, s0, v[22:23]
	v_cmp_lt_i32_e64 s[8:9], 11, v0
	v_mul_lo_u32 v46, v2, 24
	v_readlane_b32 s68, v254, 12
	v_cndmask_b32_e64 v29, 0, -12, s[8:9]
	v_sub_u32_e32 v0, v29, v46
	v_readlane_b32 s74, v254, 18
	v_readlane_b32 s75, v254, 19
	v_add_u32_e32 v47, s52, v2
	v_add_u32_e32 v28, v22, v0
	v_mov_b64_e32 v[0:1], s[74:75]
	v_mad_i64_i32 v[2:3], s[0:1], v47, s97, v[0:1]
	v_cndmask_b32_e64 v112, v123, v124, s[8:9]
	v_lshlrev_b32_e32 v4, 7, v28
	v_lshl_add_u64 v[2:3], v[2:3], 0, v[112:113]
	v_ashrrev_i32_e32 v5, 31, v4
	v_lshl_add_u64 v[2:3], v[4:5], 1, v[2:3]
	v_lshlrev_b32_e32 v112, 1, v16
	v_lshl_add_u64 v[2:3], v[2:3], 0, v[112:113]
	global_load_dwordx4 v[12:15], v[2:3], off
	v_add_u32_e32 v2, 8, v17
	v_mul_hi_i32 v3, v2, s66
	v_lshrrev_b32_e32 v4, 31, v3
	v_add_u32_e32 v3, v3, v4
	v_mul_lo_u32 v4, v3, 6
	v_sub_u32_e32 v2, v2, v4
	v_lshl_or_b32 v2, v2, 2, v23
	v_cmp_lt_i32_e64 s[6:7], 11, v2
	v_add_u32_e32 v45, s52, v3
	v_mov_b32_e32 v5, v113
	v_cndmask_b32_e64 v3, 0, -12, s[6:7]
	v_add_u32_e32 v44, v3, v2
	v_mad_i64_i32 v[2:3], s[0:1], v45, s97, v[0:1]
	v_cndmask_b32_e64 v4, v123, v124, s[6:7]
	v_lshl_add_u64 v[2:3], v[2:3], 0, v[4:5]
	v_lshlrev_b32_e32 v4, 7, v44
	v_ashrrev_i32_e32 v5, 31, v4
	v_lshl_add_u64 v[2:3], v[4:5], 1, v[2:3]
	v_lshl_add_u64 v[2:3], v[2:3], 0, v[112:113]
	global_load_dwordx4 v[4:7], v[2:3], off
	v_add_u32_e32 v2, 16, v17
	v_mul_hi_i32 v3, v2, s66
	v_lshrrev_b32_e32 v8, 31, v3
	v_add_u32_e32 v3, v3, v8
	v_mul_lo_u32 v8, v3, 6
	v_sub_u32_e32 v2, v2, v8
	v_lshl_or_b32 v2, v2, 2, v23
	v_cmp_lt_i32_e64 s[4:5], 11, v2
	v_add_u32_e32 v43, s52, v3
	v_mad_i64_i32 v[0:1], s[0:1], v43, s97, v[0:1]
	v_cndmask_b32_e64 v3, 0, -12, s[4:5]
	v_add_u32_e32 v42, v3, v2
	v_cndmask_b32_e64 v2, v123, v124, s[4:5]
	v_mov_b32_e32 v3, v113
	v_lshl_add_u64 v[0:1], v[0:1], 0, v[2:3]
	v_lshlrev_b32_e32 v2, 7, v42
	v_ashrrev_i32_e32 v3, 31, v2
	v_lshl_add_u64 v[0:1], v[2:3], 1, v[0:1]
	v_lshl_add_u64 v[0:1], v[0:1], 0, v[112:113]
	global_load_dwordx4 v[0:3], v[0:1], off
	v_cmp_gt_i32_e64 s[10:11], 10, v28
	v_cmp_gt_i32_e64 s[12:13], 8, v28
	v_cmp_lt_i32_e64 s[14:15], 7, v28
	s_and_b64 s[0:1], s[8:9], s[10:11]
	v_readlane_b32 s69, v254, 13
	v_readlane_b32 s70, v254, 14
	v_readlane_b32 s71, v254, 15
	v_readlane_b32 s72, v254, 16
	v_readlane_b32 s73, v254, 17
	v_readlane_b32 s76, v254, 20
	v_readlane_b32 s77, v254, 21
	v_readlane_b32 s78, v254, 22
	v_readlane_b32 s79, v254, 23
	v_readlane_b32 s80, v254, 24
	v_readlane_b32 s81, v254, 25
	v_readlane_b32 s82, v254, 26
	v_readlane_b32 s83, v254, 27
	v_lshlrev_b32_e32 v210, 2, v16
	v_mov_b32_e32 v211, 0
	v_cmp_gt_i32_e64 s[98:99], 8, v28
	v_mov_b32_e32 v206, s34
	v_mov_b32_e32 v207, s2
	v_mov_b32_e32 v208, s35
	v_mov_b32_e32 v209, s3
	v_cndmask_b32_e64 v206, v207, v206, s[98:99]
	v_cndmask_b32_e64 v207, v209, v208, s[98:99]
	v_lshl_add_u64 v[206:207], v[206:207], 0, v[210:211]
	global_load_dwordx4 v[130:133], v[206:207], off offset:512
	global_load_dwordx4 v[134:137], v[206:207], off offset:528
	s_cbranch_vccz .Lprepb_norope0
	v_and_b32_e32 v208, s56, v47
	v_lshlrev_b32_e32 v208, 9, v208
	v_mov_b32_e32 v209, 0
	v_lshl_add_u64 v[208:209], v[20:21], 0, v[208:209]
	global_load_dwordx4 v[138:141], v[208:209], off offset:48
	global_load_dwordx4 v[142:145], v[208:209], off offset:32
	global_load_dwordx4 v[146:149], v[208:209], off offset:16
	global_load_dwordx4 v[150:153], v[208:209], off
.Lprepb_norope0:
	v_cmp_gt_i32_e64 s[98:99], 8, v44
	v_mov_b32_e32 v206, s34
	v_mov_b32_e32 v207, s2
	v_mov_b32_e32 v208, s35
	v_mov_b32_e32 v209, s3
	v_cndmask_b32_e64 v206, v207, v206, s[98:99]
	v_cndmask_b32_e64 v207, v209, v208, s[98:99]
	v_lshl_add_u64 v[206:207], v[206:207], 0, v[210:211]
	global_load_dwordx4 v[154:157], v[206:207], off offset:512
	global_load_dwordx4 v[158:161], v[206:207], off offset:528
	s_cbranch_vccz .Lprepb_norope1
	v_and_b32_e32 v208, s56, v45
	v_lshlrev_b32_e32 v208, 9, v208
	v_mov_b32_e32 v209, 0
	v_lshl_add_u64 v[208:209], v[20:21], 0, v[208:209]
	global_load_dwordx4 v[162:165], v[208:209], off offset:48
	global_load_dwordx4 v[166:169], v[208:209], off offset:32
	global_load_dwordx4 v[170:173], v[208:209], off offset:16
	global_load_dwordx4 v[174:177], v[208:209], off
.Lprepb_norope1:
	v_cmp_gt_i32_e64 s[98:99], 8, v42
	v_mov_b32_e32 v206, s34
	v_mov_b32_e32 v207, s2
	v_mov_b32_e32 v208, s35
	v_mov_b32_e32 v209, s3
	v_cndmask_b32_e64 v206, v207, v206, s[98:99]
	v_cndmask_b32_e64 v207, v209, v208, s[98:99]
	v_lshl_add_u64 v[206:207], v[206:207], 0, v[210:211]
	global_load_dwordx4 v[182:185], v[206:207], off offset:512
	global_load_dwordx4 v[186:189], v[206:207], off offset:528
	s_cbranch_vccz .Lprepb_norope2
	v_and_b32_e32 v208, s56, v43
	v_lshlrev_b32_e32 v208, 9, v208
	v_mov_b32_e32 v209, 0
	v_lshl_add_u64 v[208:209], v[20:21], 0, v[208:209]
	global_load_dwordx4 v[190:193], v[208:209], off offset:48
	global_load_dwordx4 v[194:197], v[208:209], off offset:32
	global_load_dwordx4 v[198:201], v[208:209], off offset:16
	global_load_dwordx4 v[202:205], v[208:209], off
.Lprepb_norope2:
	s_waitcnt vmcnt(0)
	v_lshlrev_b32_e32 v8, 16, v12
	v_and_b32_e32 v9, 0xffff0000, v12
	v_lshlrev_b32_e32 v10, 16, v13
	v_and_b32_e32 v11, 0xffff0000, v13
	v_pk_mul_f32 v[24:25], v[8:9], v[8:9]
	v_pk_mul_f32 v[26:27], v[10:11], v[10:11]
	v_add_f32_e32 v24, v24, v25
	v_lshlrev_b32_e32 v12, 16, v14
	v_and_b32_e32 v13, 0xffff0000, v14
	v_add_f32_e32 v24, v24, v26
	v_pk_mul_f32 v[30:31], v[12:13], v[12:13]
	v_add_f32_e32 v24, v27, v24
	v_lshlrev_b32_e32 v14, 16, v15
	v_and_b32_e32 v15, 0xffff0000, v15
	v_add_f32_e32 v24, v30, v24
	v_pk_mul_f32 v[32:33], v[14:15], v[14:15]
	v_add_f32_e32 v24, v31, v24
	v_add_f32_e32 v24, v32, v24
	v_add_f32_e32 v24, v33, v24
	ds_bpermute_b32 v25, v37, v24
	s_waitcnt lgkmcnt(0)
	v_add_f32_e32 v24, v24, v25
	ds_bpermute_b32 v25, v38, v24
	s_waitcnt lgkmcnt(0)
	v_add_f32_e32 v24, v24, v25
	ds_bpermute_b32 v25, v39, v24
	s_waitcnt lgkmcnt(0)
	v_add_f32_e32 v25, v24, v25
	ds_bpermute_b32 v26, v40, v25
	v_lshlrev_b32_e32 v24, 2, v16
	s_and_saveexec_b64 s[58:59], s[0:1]
	s_cbranch_execz .LBB0_1013
	s_waitcnt lgkmcnt(0)
	v_add_f32_e32 v25, v25, v26
	v_fmamk_f32 v25, v25, 0x3c000000, v115
	v_cmp_gt_f32_e64 s[0:1], s67, v25
	v_mul_f32_e32 v26, 0x4b800000, v25
	v_mov_b32_e32 v27, s35
	v_cndmask_b32_e64 v25, v25, v26, s[0:1]
	v_rsq_f32_e32 v25, v25
	s_nop 0
	v_mul_f32_e32 v26, 0x45800000, v25
	v_cndmask_b32_e64 v26, v25, v26, s[0:1]
	v_mov_b32_e32 v25, s3
	v_cndmask_b32_e64 v31, v25, v27, s[12:13]
	v_mov_b32_e32 v25, s2
	v_mov_b32_e32 v27, s34
	v_cndmask_b32_e64 v30, v25, v27, s[12:13]
	v_mov_b32_e32 v25, v113
	v_lshl_add_u64 v[34:35], v[30:31], 0, v[24:25]
	v_mov_b32_e32 v30, v130
	v_mov_b32_e32 v31, v131
	v_mov_b32_e32 v32, v132
	v_mov_b32_e32 v33, v133
	v_mov_b32_e32 v48, v134
	v_mov_b32_e32 v49, v135
	v_mov_b32_e32 v50, v136
	v_mov_b32_e32 v51, v137
	v_pk_mul_f32 v[32:33], v[26:27], v[32:33] op_sel_hi:[0,1]
	v_pk_mul_f32 v[34:35], v[26:27], v[50:51] op_sel_hi:[0,1]
	v_pk_mul_f32 v[30:31], v[26:27], v[30:31] op_sel_hi:[0,1]
	v_pk_mul_f32 v[26:27], v[26:27], v[48:49] op_sel_hi:[0,1]
	v_pk_mul_f32 v[14:15], v[34:35], v[14:15]
	v_pk_mul_f32 v[10:11], v[32:33], v[10:11]
	v_pk_mul_f32 v[12:13], v[26:27], v[12:13]
	v_pk_mul_f32 v[8:9], v[30:31], v[8:9]
.LBB0_1013:
	s_or_b64 exec, exec, s[58:59]
	ds_bpermute_b32 v34, v39, v8
	ds_bpermute_b32 v35, v39, v9
	ds_bpermute_b32 v32, v39, v10
	ds_bpermute_b32 v33, v39, v11
	ds_bpermute_b32 v30, v39, v12
	ds_bpermute_b32 v31, v39, v13
	ds_bpermute_b32 v48, v39, v14
	ds_bpermute_b32 v25, v39, v15
	v_and_b32_e32 v28, s56, v47
	s_and_b64 s[58:59], vcc, s[10:11]
	s_waitcnt lgkmcnt(8)
	v_lshlrev_b32_e32 v26, 9, v28
	s_and_saveexec_b64 s[0:1], s[58:59]
	s_cbranch_execz .LBB0_1015
	v_mov_b32_e32 v27, v113
	v_lshl_add_u64 v[62:63], v[20:21], 0, v[26:27]
	v_mov_b32_e32 v50, v138
	v_mov_b32_e32 v51, v139
	v_mov_b32_e32 v52, v140
	v_mov_b32_e32 v53, v141
	v_mov_b32_e32 v54, v142
	v_mov_b32_e32 v55, v143
	v_mov_b32_e32 v56, v144
	v_mov_b32_e32 v57, v145
	v_mov_b32_e32 v58, v146
	v_mov_b32_e32 v59, v147
	v_mov_b32_e32 v60, v148
	v_mov_b32_e32 v61, v149
	v_mov_b32_e32 v62, v150
	v_mov_b32_e32 v63, v151
	v_mov_b32_e32 v64, v152
	v_mov_b32_e32 v65, v153
	s_waitcnt lgkmcnt(1)
	v_mul_f32_e32 v27, v18, v48
	v_pk_mul_f32 v[34:35], v[18:19], v[34:35]
	v_pk_mul_f32 v[32:33], v[18:19], v[32:33]
	v_pk_mul_f32 v[30:31], v[18:19], v[30:31]
	s_nop 0
	v_mul_f32_e32 v14, v14, v50
	v_mul_f32_e32 v48, v27, v51
	s_waitcnt lgkmcnt(0)
	v_mul_f32_e32 v51, v18, v25
	v_mov_b32_e32 v50, v15
	s_nop 0
	v_mov_b32_e32 v67, v64
	v_mov_b32_e32 v64, v63
	v_mov_b32_e32 v63, v60
	v_mov_b32_e32 v60, v59
	v_mov_b32_e32 v59, v56
	v_mov_b32_e32 v56, v55
	v_pk_mul_f32 v[50:51], v[50:51], v[52:53]
	v_mov_b32_e32 v66, v62
	v_pk_mul_f32 v[34:35], v[34:35], v[64:65]
	v_mov_b32_e32 v62, v58
	v_pk_mul_f32 v[32:33], v[32:33], v[60:61]
	v_mov_b32_e32 v58, v54
	v_pk_mul_f32 v[30:31], v[30:31], v[56:57]
	v_mov_b32_e32 v15, v50
	v_mov_b32_e32 v49, v51
	v_pk_fma_f32 v[8:9], v[8:9], v[66:67], v[34:35]
	v_pk_fma_f32 v[10:11], v[10:11], v[62:63], v[32:33]
	v_pk_fma_f32 v[12:13], v[12:13], v[58:59], v[30:31]
	v_pk_add_f32 v[14:15], v[14:15], v[48:49]

.LBB0_1027:
	s_or_b64 exec, exec, s[0:1]
	v_lshlrev_b32_e32 v8, 16, v4
	v_and_b32_e32 v9, 0xffff0000, v4
	v_lshlrev_b32_e32 v10, 16, v5
	v_and_b32_e32 v11, 0xffff0000, v5
	v_pk_mul_f32 v[12:13], v[8:9], v[8:9]
	v_pk_mul_f32 v[14:15], v[10:11], v[10:11]
	v_add_f32_e32 v12, v12, v13
	v_lshlrev_b32_e32 v4, 16, v6
	v_and_b32_e32 v5, 0xffff0000, v6
	v_add_f32_e32 v12, v12, v14
	v_pk_mul_f32 v[26:27], v[4:5], v[4:5]
	v_add_f32_e32 v12, v15, v12
	v_lshlrev_b32_e32 v6, 16, v7
	v_and_b32_e32 v7, 0xffff0000, v7
	v_add_f32_e32 v12, v26, v12
	v_pk_mul_f32 v[28:29], v[6:7], v[6:7]
	v_add_f32_e32 v12, v27, v12
	v_add_f32_e32 v12, v28, v12
	v_add_f32_e32 v12, v29, v12
	ds_bpermute_b32 v13, v37, v12
	v_cmp_gt_i32_e64 s[8:9], 10, v44
	v_cmp_gt_i32_e64 s[10:11], 8, v44
	v_cmp_lt_i32_e64 s[12:13], 7, v44
	s_and_b64 s[0:1], s[6:7], s[8:9]
	s_waitcnt lgkmcnt(0)
	v_add_f32_e32 v12, v12, v13
	ds_bpermute_b32 v13, v38, v12
	s_waitcnt lgkmcnt(0)
	v_add_f32_e32 v12, v12, v13
	ds_bpermute_b32 v13, v39, v12
	s_waitcnt lgkmcnt(0)
	v_add_f32_e32 v12, v12, v13
	ds_bpermute_b32 v13, v40, v12
	s_and_saveexec_b64 s[14:15], s[0:1]
	s_cbranch_execz .LBB0_1029
	s_waitcnt lgkmcnt(0)
	v_add_f32_e32 v12, v12, v13
	v_fmamk_f32 v12, v12, 0x3c000000, v115
	v_cmp_gt_f32_e64 s[0:1], s67, v12
	v_mul_f32_e32 v13, 0x4b800000, v12
	v_mov_b32_e32 v14, s34
	v_cndmask_b32_e64 v12, v12, v13, s[0:1]
	v_rsq_f32_e32 v12, v12
	v_mov_b32_e32 v25, v113
	v_mul_f32_e32 v13, 0x45800000, v12
	v_cndmask_b32_e64 v30, v12, v13, s[0:1]
	v_mov_b32_e32 v12, s3
	v_mov_b32_e32 v13, s35
	v_cndmask_b32_e64 v13, v12, v13, s[10:11]
	v_mov_b32_e32 v12, s2
	v_cndmask_b32_e64 v12, v12, v14, s[10:11]
	v_lshl_add_u64 v[26:27], v[12:13], 0, v[24:25]
	v_mov_b32_e32 v12, v154
	v_mov_b32_e32 v13, v155
	v_mov_b32_e32 v14, v156
	v_mov_b32_e32 v15, v157
	v_mov_b32_e32 v26, v158
	v_mov_b32_e32 v27, v159
	v_mov_b32_e32 v28, v160
	v_mov_b32_e32 v29, v161
	v_pk_mul_f32 v[14:15], v[30:31], v[14:15] op_sel_hi:[0,1]
	v_pk_mul_f32 v[28:29], v[30:31], v[28:29] op_sel_hi:[0,1]
	v_pk_mul_f32 v[12:13], v[30:31], v[12:13] op_sel_hi:[0,1]
	v_pk_mul_f32 v[26:27], v[30:31], v[26:27] op_sel_hi:[0,1]
	v_pk_mul_f32 v[6:7], v[28:29], v[6:7]
	v_pk_mul_f32 v[10:11], v[14:15], v[10:11]
	v_pk_mul_f32 v[4:5], v[26:27], v[4:5]
	v_pk_mul_f32 v[8:9], v[12:13], v[8:9]
.LBB0_1029:
	s_or_b64 exec, exec, s[14:15]
	ds_bpermute_b32 v30, v39, v8
	ds_bpermute_b32 v31, v39, v9
	ds_bpermute_b32 v28, v39, v10
	ds_bpermute_b32 v29, v39, v11
	ds_bpermute_b32 v26, v39, v4
	ds_bpermute_b32 v27, v39, v5
	ds_bpermute_b32 v25, v39, v6
	ds_bpermute_b32 v15, v39, v7
	v_and_b32_e32 v14, s56, v45
	s_and_b64 s[14:15], vcc, s[8:9]
	v_lshlrev_b32_e32 v12, 9, v14
	s_and_saveexec_b64 s[0:1], s[14:15]
	s_cbranch_execz .LBB0_1031
	s_waitcnt lgkmcnt(0)
	v_mov_b32_e32 v13, v113
	v_lshl_add_u64 v[54:55], v[20:21], 0, v[12:13]
	v_mov_b32_e32 v32, v162
	v_mov_b32_e32 v33, v163
	v_mov_b32_e32 v34, v164
	v_mov_b32_e32 v35, v165
	v_mov_b32_e32 v46, v166
	v_mov_b32_e32 v47, v167
	v_mov_b32_e32 v48, v168
	v_mov_b32_e32 v49, v169
	v_mov_b32_e32 v50, v170
	v_mov_b32_e32 v51, v171
	v_mov_b32_e32 v52, v172
	v_mov_b32_e32 v53, v173
	v_mov_b32_e32 v54, v174
	v_mov_b32_e32 v55, v175
	v_mov_b32_e32 v56, v176
	v_mov_b32_e32 v57, v177
	v_pk_mul_f32 v[30:31], v[18:19], v[30:31]
	v_pk_mul_f32 v[28:29], v[18:19], v[28:29]
	v_pk_mul_f32 v[26:27], v[18:19], v[26:27]
	v_mul_f32_e32 v13, v18, v25
	s_nop 0
	v_mul_f32_e32 v6, v6, v32
	v_mul_f32_e32 v32, v13, v33
	v_mov_b32_e32 v58, v54
	v_mov_b32_e32 v59, v56
	v_mov_b32_e32 v56, v55
	v_mov_b32_e32 v54, v50
	v_mov_b32_e32 v55, v52
	v_mov_b32_e32 v52, v51
	v_mov_b32_e32 v50, v46
	v_mov_b32_e32 v51, v48
	v_mov_b32_e32 v48, v47
	v_mul_f32_e32 v47, v18, v15
	v_mov_b32_e32 v46, v7
	v_pk_mul_f32 v[34:35], v[46:47], v[34:35]
	v_pk_mul_f32 v[30:31], v[30:31], v[56:57]
	v_pk_mul_f32 v[28:29], v[28:29], v[52:53]
	v_pk_mul_f32 v[26:27], v[26:27], v[48:49]
	v_mov_b32_e32 v7, v34
	v_mov_b32_e32 v33, v35
	v_pk_fma_f32 v[8:9], v[8:9], v[58:59], v[30:31]
	v_pk_fma_f32 v[10:11], v[10:11], v[54:55], v[28:29]
	v_pk_fma_f32 v[4:5], v[4:5], v[50:51], v[26:27]
	v_pk_add_f32 v[6:7], v[6:7], v[32:33]

.LBB0_1043:
	s_or_b64 exec, exec, s[0:1]
	s_nop 0
	v_lshlrev_b32_e32 v4, 16, v0
	v_and_b32_e32 v5, 0xffff0000, v0
	v_lshlrev_b32_e32 v6, 16, v1
	v_and_b32_e32 v7, 0xffff0000, v1
	v_pk_mul_f32 v[8:9], v[4:5], v[4:5]
	v_pk_mul_f32 v[10:11], v[6:7], v[6:7]
	v_add_f32_e32 v8, v8, v9
	v_lshlrev_b32_e32 v0, 16, v2
	v_and_b32_e32 v1, 0xffff0000, v2
	v_add_f32_e32 v8, v8, v10
	v_pk_mul_f32 v[12:13], v[0:1], v[0:1]
	v_add_f32_e32 v8, v11, v8
	v_lshlrev_b32_e32 v2, 16, v3
	v_and_b32_e32 v3, 0xffff0000, v3
	v_add_f32_e32 v8, v12, v8
	v_pk_mul_f32 v[14:15], v[2:3], v[2:3]
	v_add_f32_e32 v8, v13, v8
	v_add_f32_e32 v8, v14, v8
	v_add_f32_e32 v8, v15, v8
	ds_bpermute_b32 v9, v37, v8
	v_cmp_gt_i32_e64 s[6:7], 10, v42
	v_cmp_gt_i32_e64 s[8:9], 8, v42
	v_cmp_lt_i32_e64 s[10:11], 7, v42
	s_and_b64 s[0:1], s[4:5], s[6:7]
	s_waitcnt lgkmcnt(0)
	v_add_f32_e32 v8, v8, v9
	ds_bpermute_b32 v9, v38, v8
	s_waitcnt lgkmcnt(0)
	v_add_f32_e32 v8, v8, v9
	ds_bpermute_b32 v9, v39, v8
	s_waitcnt lgkmcnt(0)
	v_add_f32_e32 v8, v8, v9
	ds_bpermute_b32 v9, v40, v8
	s_and_saveexec_b64 s[12:13], s[0:1]
	s_cbranch_execz .LBB0_1045
	s_waitcnt lgkmcnt(0)
	v_add_f32_e32 v8, v8, v9
	v_fmamk_f32 v8, v8, 0x3c000000, v115
	v_cmp_gt_f32_e64 s[0:1], s67, v8
	v_mul_f32_e32 v9, 0x4b800000, v8
	v_mov_b32_e32 v10, s34
	v_cndmask_b32_e64 v8, v8, v9, s[0:1]
	v_rsq_f32_e32 v8, v8
	v_mov_b32_e32 v25, v113
	v_mul_f32_e32 v9, 0x45800000, v8
	v_cndmask_b32_e64 v26, v8, v9, s[0:1]
	v_mov_b32_e32 v8, s3
	v_mov_b32_e32 v9, s35
	v_cndmask_b32_e64 v9, v8, v9, s[8:9]
	v_mov_b32_e32 v8, s2
	v_cndmask_b32_e64 v8, v8, v10, s[8:9]
	v_lshl_add_u64 v[12:13], v[8:9], 0, v[24:25]
	v_mov_b32_e32 v8, v182
	v_mov_b32_e32 v9, v183
	v_mov_b32_e32 v10, v184
	v_mov_b32_e32 v11, v185
	v_mov_b32_e32 v12, v186
	v_mov_b32_e32 v13, v187
	v_mov_b32_e32 v14, v188
	v_mov_b32_e32 v15, v189
	v_pk_mul_f32 v[10:11], v[26:27], v[10:11] op_sel_hi:[0,1]
	v_pk_mul_f32 v[14:15], v[26:27], v[14:15] op_sel_hi:[0,1]
	v_pk_mul_f32 v[8:9], v[26:27], v[8:9] op_sel_hi:[0,1]
	v_pk_mul_f32 v[12:13], v[26:27], v[12:13] op_sel_hi:[0,1]
	v_pk_mul_f32 v[2:3], v[14:15], v[2:3]
	v_pk_mul_f32 v[6:7], v[10:11], v[6:7]
	v_pk_mul_f32 v[0:1], v[12:13], v[0:1]
	v_pk_mul_f32 v[4:5], v[8:9], v[4:5]
.LBB0_1045:
	s_or_b64 exec, exec, s[12:13]
	ds_bpermute_b32 v26, v39, v4
	ds_bpermute_b32 v27, v39, v5
	ds_bpermute_b32 v14, v39, v6
	ds_bpermute_b32 v15, v39, v7
	ds_bpermute_b32 v12, v39, v0
	ds_bpermute_b32 v13, v39, v1
	ds_bpermute_b32 v25, v39, v2
	ds_bpermute_b32 v11, v39, v3
	v_and_b32_e32 v10, s56, v43
	s_and_b64 s[12:13], vcc, s[6:7]
	v_lshlrev_b32_e32 v8, 9, v10
	s_and_saveexec_b64 s[0:1], s[12:13]
	s_cbranch_execz .LBB0_1047
	s_waitcnt lgkmcnt(0)
	v_mov_b32_e32 v9, v113
	v_lshl_add_u64 v[48:49], v[20:21], 0, v[8:9]
	v_mov_b32_e32 v28, v190
	v_mov_b32_e32 v29, v191
	v_mov_b32_e32 v30, v192
	v_mov_b32_e32 v31, v193
	v_mov_b32_e32 v32, v194
	v_mov_b32_e32 v33, v195
	v_mov_b32_e32 v34, v196
	v_mov_b32_e32 v35, v197
	v_mov_b32_e32 v44, v198
	v_mov_b32_e32 v45, v199
	v_mov_b32_e32 v46, v200
	v_mov_b32_e32 v47, v201
	v_mov_b32_e32 v48, v202
	v_mov_b32_e32 v49, v203
	v_mov_b32_e32 v50, v204
	v_mov_b32_e32 v51, v205
	v_pk_mul_f32 v[26:27], v[18:19], v[26:27]
	v_pk_mul_f32 v[14:15], v[18:19], v[14:15]
	v_pk_mul_f32 v[12:13], v[18:19], v[12:13]
	v_mul_f32_e32 v9, v18, v25
	s_nop 0
	v_mul_f32_e32 v2, v2, v28
	v_mul_f32_e32 v28, v9, v29
	v_mov_b32_e32 v52, v48
	v_mov_b32_e32 v53, v50
	v_mov_b32_e32 v50, v49
	v_mov_b32_e32 v48, v44
	v_mov_b32_e32 v49, v46
	v_mov_b32_e32 v46, v45
	v_mov_b32_e32 v44, v32
	v_mov_b32_e32 v45, v34
	v_mov_b32_e32 v34, v33
	v_mul_f32_e32 v33, v18, v11
	v_mov_b32_e32 v32, v3
	v_pk_mul_f32 v[30:31], v[32:33], v[30:31]
	v_pk_mul_f32 v[26:27], v[26:27], v[50:51]
	v_pk_mul_f32 v[14:15], v[14:15], v[46:47]
	v_pk_mul_f32 v[12:13], v[12:13], v[34:35]
	v_mov_b32_e32 v3, v30
	v_mov_b32_e32 v29, v31
	v_pk_fma_f32 v[4:5], v[4:5], v[52:53], v[26:27]
	v_pk_fma_f32 v[6:7], v[6:7], v[48:49], v[14:15]
	v_pk_fma_f32 v[0:1], v[0:1], v[44:45], v[12:13]
	v_pk_add_f32 v[2:3], v[2:3], v[28:29]
